# all four row loads in flight in the bf16 RMSNorm loops; fnet_combine loads no longer wait for previous stores
# baseline (speedup 1.0000x reference)
; __device__ __forceinline__ unsigned cvt_pk_bf16(float lo, float hi) { const f32x2_t v = {lo, hi}; const bf16x2_t b = __builtin_convertvector(v, bf16x2_t); return __builtin_bit_cast(unsigned, b); }
; __device__ void rmsnorm_phase(const float* __restrict__ x, const float* __restrict__ g, bf16_t* h, float* outf) {
;     ...
;     for (int row = gw; row < T_; row += nw) {
;         const float4* xr = (const float4*)(x + (size_t)row * D_);
;         float4 v[4]; float ss = 0.f;
; #pragma unroll
;         for (int i = 0; i < 4; ++i) { v[i] = xr[lane + 64 * i]; ss += v[i].x * v[i].x + v[i].y * v[i].y + v[i].z * v[i].z + v[i].w * v[i].w; }
; #pragma unroll
;         for (int o = 32; o >= 1; o >>= 1) ss += __shfl_xor(ss, o);
;         const float rs = rsqrtf(ss * (1.0f / 1024.0f) + 1e-6f);
; #pragma unroll
;         for (int i = 0; i < 4; ++i) {
;             const float a = v[i].x * rs * gv[i].x, b = v[i].y * rs * gv[i].y, c = v[i].z * rs * gv[i].z, d = v[i].w * rs * gv[i].w;
;             if (outf) ((float4*)(outf + (size_t)row * D_))[lane + 64 * i] = make_float4(a, b, c, d);
;             else { u32x2 w; w.x = cvt_pk_bf16(a, b); w.y = cvt_pk_bf16(c, d); *(u32x2*)(h + (size_t)row * D_ + (lane + 64 * i) * 4) = w; }
;         }
.LBB0_81:
	global_load_dwordx4 v[30:33], v[22:23], off
	global_load_dwordx4 v[34:37], v[22:23], off offset:1024
	global_load_dwordx4 v[56:59], v[22:23], off offset:2048
	global_load_dwordx4 v[60:63], v[22:23], off offset:3072
	v_add_u32_e32 v18, s4, v18
	s_waitcnt vmcnt(2)
	v_mov_b32_e32 v44, v31
	v_mov_b32_e32 v45, v35
	v_mov_b32_e32 v42, v30
	v_mov_b32_e32 v43, v34
	v_pk_mul_f32 v[44:45], v[44:45], v[44:45]
	v_mov_b32_e32 v38, v32
	v_mov_b32_e32 v39, v36
	v_pk_fma_f32 v[42:43], v[42:43], v[42:43], v[44:45]
	v_mov_b32_e32 v40, v33
	v_mov_b32_e32 v41, v37
	v_pk_fma_f32 v[38:39], v[38:39], v[38:39], v[42:43]
	s_nop 0
	v_pk_fma_f32 v[46:47], v[40:41], v[40:41], v[38:39]
	v_add_f32_e32 v19, v46, v47
	v_lshl_add_u64 v[22:23], v[22:23], 0, s[8:9]
	s_waitcnt vmcnt(0)
	v_mov_b32_e32 v54, v57
	v_mov_b32_e32 v55, v61
	v_mov_b32_e32 v52, v56
	v_mov_b32_e32 v53, v60
	v_pk_mul_f32 v[54:55], v[54:55], v[54:55]
	v_mov_b32_e32 v48, v58
	v_mov_b32_e32 v49, v62
	v_pk_fma_f32 v[52:53], v[52:53], v[52:53], v[54:55]
	v_mov_b32_e32 v50, v59
	v_mov_b32_e32 v51, v63
	v_pk_fma_f32 v[48:49], v[48:49], v[48:49], v[52:53]
	s_nop 0
	v_pk_fma_f32 v[48:49], v[50:51], v[50:51], v[48:49]
	s_nop 0
	v_add_f32_e32 v19, v19, v48
	v_add_f32_e32 v19, v19, v49
	ds_bpermute_b32 v29, v0, v19
	s_waitcnt lgkmcnt(0)
	v_add_f32_e32 v19, v19, v29
	ds_bpermute_b32 v29, v24, v19
	s_waitcnt lgkmcnt(0)
	v_add_f32_e32 v19, v19, v29
	ds_bpermute_b32 v29, v25, v19
	s_waitcnt lgkmcnt(0)
	v_add_f32_e32 v19, v19, v29
	ds_bpermute_b32 v29, v26, v19
	s_waitcnt lgkmcnt(0)
	v_add_f32_e32 v19, v19, v29
	ds_bpermute_b32 v29, v27, v19
	s_waitcnt lgkmcnt(0)
	v_add_f32_e32 v19, v19, v29
	ds_bpermute_b32 v29, v28, v19
	s_waitcnt lgkmcnt(0)
	v_add_f32_e32 v19, v19, v29
	v_fmamk_f32 v19, v19, 0x3a800000, v169
	v_cmp_gt_f32_e32 vcc, s33, v19
	v_mul_f32_e32 v29, 0x4b800000, v19
	s_nop 0
	v_cndmask_b32_e32 v19, v19, v29, vcc
	v_rsq_f32_e32 v19, v19
	s_nop 0
	v_mul_f32_e32 v29, 0x45800000, v19
	v_cndmask_b32_e32 v46, v19, v29, vcc
	v_pk_mul_f32 v[30:31], v[30:31], v[46:47] op_sel_hi:[1,0]
	v_pk_mul_f32 v[32:33], v[32:33], v[46:47] op_sel_hi:[1,0]
	v_pk_mul_f32 v[30:31], v[2:3], v[30:31]
	v_pk_mul_f32 v[32:33], v[4:5], v[32:33]
	v_cvt_pk_bf16_f32 v30, v30, v31
	v_cvt_pk_bf16_f32 v31, v32, v33
	global_store_dwordx2 v[20:21], v[30:31], off
	v_pk_mul_f32 v[30:31], v[34:35], v[46:47] op_sel_hi:[1,0]
	v_pk_mul_f32 v[32:33], v[36:37], v[46:47] op_sel_hi:[1,0]
	v_pk_mul_f32 v[30:31], v[6:7], v[30:31]
	v_pk_mul_f32 v[32:33], v[8:9], v[32:33]
	v_cvt_pk_bf16_f32 v30, v30, v31
	v_cvt_pk_bf16_f32 v31, v32, v33
	global_store_dwordx2 v[20:21], v[30:31], off offset:512
	v_pk_mul_f32 v[30:31], v[56:57], v[46:47] op_sel_hi:[1,0]
	v_pk_mul_f32 v[32:33], v[58:59], v[46:47] op_sel_hi:[1,0]
	v_pk_mul_f32 v[30:31], v[10:11], v[30:31]
	v_pk_mul_f32 v[32:33], v[12:13], v[32:33]
	v_cvt_pk_bf16_f32 v30, v30, v31
	v_cvt_pk_bf16_f32 v31, v32, v33
	global_store_dwordx2 v[20:21], v[30:31], off offset:1024
	v_pk_mul_f32 v[30:31], v[60:61], v[46:47] op_sel_hi:[1,0]
	v_pk_mul_f32 v[32:33], v[62:63], v[46:47] op_sel_hi:[1,0]
	v_pk_mul_f32 v[30:31], v[14:15], v[30:31]
	v_pk_mul_f32 v[32:33], v[16:17], v[32:33]
	v_cvt_pk_bf16_f32 v30, v30, v31
	v_cvt_pk_bf16_f32 v31, v32, v33
	v_cmp_lt_i32_e32 vcc, s59, v18
	global_store_dwordx2 v[20:21], v[30:31], off offset:1536
	v_lshl_add_u64 v[20:21], v[20:21], 0, s[6:7]
	s_or_b64 s[10:11], vcc, s[10:11]
	s_andn2_b64 exec, exec, s[10:11]
	s_cbranch_execnz .LBB0_81

; __device__ __forceinline__ uint4 pack8(const float (&f)[8]) { uint4 r; r.x = cvt_pk_bf16(f[0], f[1]); r.y = cvt_pk_bf16(f[2], f[3]); r.z = cvt_pk_bf16(f[4], f[5]); r.w = cvt_pk_bf16(f[6], f[7]); return r; }
; __device__ void fnet_combine_phase(const Params& p) {
;     ...
;     for (int idx = gtid; idx < NB_ * 1024 * 64; idx += gsz) {
;         const int n8 = (idx & 63) * 8, sp = (idx >> 6) & 1023, b = idx >> 16;
;         float pf[8], qf[8], d[8], sm[8];
;         unpack8(*(const uint4*)(PQ + ((size_t)(b * 2) * 1024 + sp) * 512 + n8), pf); unpack8(*(const uint4*)(PQ + ((size_t)(b * 2 + 1) * 1024 + sp) * 512 + n8), qf);
; #pragma unroll
;         for (int j = 0; j < 8; ++j) { d[j] = pf[j] - qf[j]; sm[j] = pf[j] + qf[j]; }
;         *(uint4*)(YB + ((size_t)b * SEQ_ + sp) * 512 + n8) = pack8(d);
;         if (sp > 0) *(uint4*)(YB + ((size_t)b * SEQ_ + (SEQ_ - sp)) * 512 + n8) = pack8(sm);
;     }
.LBB0_238:
	v_ashrrev_i32_e32 v18, 16, v20
	v_lshlrev_b32_e32 v10, 1, v18
	v_ashrrev_i32_e32 v11, 31, v10
	v_lshlrev_b64 v[2:3], 20, v[10:11]
	v_or_b32_e32 v10, 1, v10
	v_ashrrev_i32_e32 v11, 31, v10
	v_bfe_u32 v22, v20, 6, 10
	v_lshlrev_b64 v[10:11], 20, v[10:11]
	v_and_b32_e32 v0, 0x1f8, v21
	v_lshl_add_u64 v[2:3], s[4:5], 0, v[2:3]
	v_lshlrev_b32_e32 v12, 10, v22
	v_mov_b32_e32 v13, v1
	v_lshl_add_u64 v[10:11], s[4:5], 0, v[10:11]
	v_lshl_add_u64 v[2:3], v[2:3], 0, v[12:13]
	v_lshlrev_b32_e32 v0, 1, v0
	v_lshl_add_u64 v[10:11], v[10:11], 0, v[12:13]
	v_lshl_add_u64 v[2:3], v[2:3], 0, v[0:1]
	v_lshl_add_u64 v[10:11], v[10:11], 0, v[0:1]
	flat_load_dwordx4 v[6:9], v[2:3]
	flat_load_dwordx4 v[14:17], v[10:11]
	v_ashrrev_i32_e32 v19, 31, v18
	v_lshlrev_b64 v[18:19], 11, v[18:19]
	v_cmp_ne_u32_e32 vcc, 0, v22
	s_waitcnt vmcnt(0) lgkmcnt(0)
	v_lshlrev_b32_e32 v2, 16, v6
	v_and_b32_e32 v3, 0xffff0000, v6
	v_lshlrev_b32_e32 v4, 16, v7
	v_and_b32_e32 v5, 0xffff0000, v7
	v_lshlrev_b32_e32 v6, 16, v8
	v_and_b32_e32 v7, 0xffff0000, v8
	v_lshlrev_b32_e32 v10, 16, v14
	v_and_b32_e32 v11, 0xffff0000, v14
	v_lshlrev_b32_e32 v12, 16, v15
	v_and_b32_e32 v13, 0xffff0000, v15
	v_lshlrev_b32_e32 v14, 16, v16
	v_and_b32_e32 v15, 0xffff0000, v16
	v_pk_add_f32 v[24:25], v[2:3], v[10:11] neg_lo:[0,1] neg_hi:[0,1]
	v_pk_add_f32 v[26:27], v[4:5], v[12:13] neg_lo:[0,1] neg_hi:[0,1]
	v_pk_add_f32 v[28:29], v[6:7], v[14:15] neg_lo:[0,1] neg_hi:[0,1]
	v_cvt_pk_bf16_f32 v24, v24, v25
	v_cvt_pk_bf16_f32 v25, v26, v27
	v_cvt_pk_bf16_f32 v26, v28, v29
	v_or_b32_e32 v28, v18, v22
	v_mov_b32_e32 v29, v19
	v_lshlrev_b32_e32 v8, 16, v9
	v_and_b32_e32 v9, 0xffff0000, v9
	v_lshlrev_b32_e32 v16, 16, v17
	v_and_b32_e32 v17, 0xffff0000, v17
	v_lshlrev_b64 v[28:29], 10, v[28:29]
	v_pk_add_f32 v[30:31], v[8:9], v[16:17] neg_lo:[0,1] neg_hi:[0,1]
	v_lshl_add_u64 v[28:29], s[6:7], 0, v[28:29]
	v_cvt_pk_bf16_f32 v27, v30, v31
	v_lshl_add_u64 v[28:29], v[28:29], 0, v[0:1]
	flat_store_dwordx4 v[28:29], v[24:27]
	s_and_saveexec_b64 s[10:11], vcc
	s_cbranch_execz .LBB0_237
	v_pk_add_f32 v[6:7], v[6:7], v[14:15]
	v_pk_add_f32 v[4:5], v[4:5], v[12:13]
	v_pk_add_f32 v[2:3], v[2:3], v[10:11]
	v_pk_add_f32 v[8:9], v[8:9], v[16:17]
	v_cvt_pk_bf16_f32 v2, v2, v3
	v_cvt_pk_bf16_f32 v3, v4, v5
	v_cvt_pk_bf16_f32 v4, v6, v7
	v_sub_u32_e32 v6, 0x800, v22
	v_mov_b32_e32 v7, v1
	v_lshl_add_u64 v[6:7], v[18:19], 0, v[6:7]
	v_lshlrev_b64 v[6:7], 10, v[6:7]
	v_lshl_add_u64 v[6:7], s[6:7], 0, v[6:7]
	v_cvt_pk_bf16_f32 v5, v8, v9
	v_lshl_add_u64 v[6:7], v[6:7], 0, v[0:1]
	flat_store_dwordx4 v[6:7], v[2:5]
	s_branch .LBB0_237
